# final RMSNorm phase: the four loop-invariant gain loads hoisted out of the row loop into v48-v63 (they were re-issued per row behind the nt output stores and waited with vmcnt(0), i.e. on the store ac
# speedup vs baseline: 1.0014x; 1.0014x over previous
; __device__ __forceinline__ void final_phase(CArgs* a, int gw, int NGW, int lane) {
;     asm volatile("" : "+v"(lane));
;     float* X = a->out; const bf16* XB = (const bf16*)(a->ws + a->ws_off + WS_XB); const float* ssp = (const float*)(a->ws + a->ws_off + WS_SSP); const float* g = a->in[23];
;     for (int mb = gw; mb < M; mb += 2 * NGW) { v4u raw[2][2]; float sp[2];
; #pragma unroll
;         for (int rr = 0; rr < 2; ++rr) { const int m = mb + rr * NGW; if (m < M) { sp[rr] = ssp[(size_t)m * 16 + (lane & 15)];
; #pragma unroll
;             for (int j = 0; j < 2; ++j) raw[rr][j] = *((const v4u*)(XB + (size_t)m * D) + lane + 64 * j); } }
; #pragma unroll
;         for (int rr = 0; rr < 2; ++rr) { const int m = mb + rr * NGW; if (m < M) { float s = sp[rr];
;             s += __shfl_xor(s, 1); s += __shfl_xor(s, 2); s += __shfl_xor(s, 4); s += __shfl_xor(s, 8);
;             const float r = __builtin_amdgcn_rsqf(s * (1.f / 1024.f) + EPS);
; #pragma unroll
;             for (int j = 0; j < 2; ++j) { const v4u w = raw[rr][j]; const int col = 8 * (lane + 64 * j);
;                 const f32x4 g0 = *(const f32x4*)(g + col), g1 = *(const f32x4*)(g + col + 4);
;                 const f32x4 v0 = (f32x4){__builtin_bit_cast(float, w.x << 16), __builtin_bit_cast(float, w.x & 0xffff0000u), __builtin_bit_cast(float, w.y << 16), __builtin_bit_cast(float, w.y & 0xffff0000u)};
;                 const f32x4 v1 = (f32x4){__builtin_bit_cast(float, w.z << 16), __builtin_bit_cast(float, w.z & 0xffff0000u), __builtin_bit_cast(float, w.w << 16), __builtin_bit_cast(float, w.w & 0xffff0000u)};
;                 __builtin_nontemporal_store(v0 * r * g0, (f32x4*)(X + (size_t)m * D + col)); __builtin_nontemporal_store(v1 * r * g1, (f32x4*)(X + (size_t)m * D + col + 4)); } } } }
.LBB0_1134:
	s_cmp_lt_u32 s2, 16
	s_cbranch_scc0 .LBB0_1144
	v_readlane_b32 s0, v252, 6
	v_readlane_b32 s1, v252, 7
	s_andn2_b64 vcc, exec, s[0:1]
	s_cbranch_vccnz .LBB0_1144
	s_load_dwordx8 s[4:11], s[92:93], 0xb8
	v_and_b32_e32 v0, 15, v144
	v_mov_b32_e32 v19, 0
	v_lshlrev_b32_e32 v18, 2, v0
	s_mov_b64 s[2:3], 0x10e00000
	s_waitcnt lgkmcnt(0)
	s_add_u32 s0, s8, s10
	s_addc_u32 s1, s9, s11
	v_lshl_add_u64 v[0:1], s[0:1], 0, v[18:19]
	v_ashrrev_i32_e32 v145, 31, v144
	v_lshl_add_u64 v[16:17], v[0:1], 0, s[2:3]
	v_lshl_add_u64 v[0:1], v[144:145], 4, s[0:1]
	s_mov_b64 s[0:1], 0x11600000
	v_and_b32_e32 v2, 64, v192
	s_waitcnt vmcnt(0)
	v_lshl_add_u64 v[20:21], v[0:1], 0, s[0:1]
	v_xor_b32_e32 v1, 1, v192
	v_add_u32_e32 v2, 64, v2
	v_cmp_lt_i32_e32 vcc, v1, v2
	v_lshlrev_b32_e32 v0, 3, v144
	v_mov_b32_e32 v29, 0x358637bd
	v_cndmask_b32_e32 v1, v192, v1, vcc
	v_lshlrev_b32_e32 v18, 2, v1
	v_xor_b32_e32 v1, 2, v192
	v_cmp_lt_i32_e32 vcc, v1, v2
	v_readlane_b32 s8, v252, 8
	v_readlane_b32 s9, v252, 9
	v_cndmask_b32_e32 v1, v192, v1, vcc
	v_lshlrev_b32_e32 v26, 2, v1
	v_xor_b32_e32 v1, 4, v192
	v_cmp_lt_i32_e32 vcc, v1, v2
	s_nop 1
	v_cndmask_b32_e32 v1, v192, v1, vcc
	v_lshlrev_b32_e32 v27, 2, v1
	v_xor_b32_e32 v1, 8, v192
	v_cmp_lt_i32_e32 vcc, v1, v2
	s_nop 1
	v_cndmask_b32_e32 v1, v192, v1, vcc
	v_lshlrev_b32_e32 v28, 2, v1
	v_ashrrev_i32_e32 v1, 31, v0
	v_lshlrev_b64 v[0:1], 2, v[0:1]
	v_lshl_add_u64 v[22:23], s[4:5], 0, v[0:1]
	v_lshl_add_u64 v[24:25], s[6:7], 0, v[0:1]
	v_readlane_b32 s6, v252, 10
	v_readlane_b32 s7, v252, 11
	global_load_dwordx4 v[48:51], v[22:23], off
	global_load_dwordx4 v[52:55], v[22:23], off offset:16
	global_load_dwordx4 v[56:59], v[22:23], off offset:2048
	global_load_dwordx4 v[60:63], v[22:23], off offset:2064
	s_waitcnt vmcnt(0)
	s_branch .LBB0_1139
.LBB0_1137:
	ds_bpermute_b32 v30, v18, v19
	s_ashr_i32 s1, s0, 31
	v_lshlrev_b32_e32 v32, 16, v5
	v_and_b32_e32 v35, 0xffff0000, v6
	v_lshlrev_b32_e32 v36, 16, v7
	s_waitcnt lgkmcnt(0)
	v_add_f32_e32 v30, v19, v30
	ds_bpermute_b32 v31, v26, v30
	s_lshl_b64 s[2:3], s[0:1], 12
	v_lshl_add_u64 v[40:41], v[24:25], 0, s[2:3]
	s_waitcnt lgkmcnt(0)
	v_add_f32_e32 v33, v30, v31
	ds_bpermute_b32 v34, v27, v33
	v_lshlrev_b32_e32 v30, 16, v4
	v_and_b32_e32 v31, 0xffff0000, v4
	s_waitcnt lgkmcnt(0)
	v_add_f32_e32 v37, v33, v34
	ds_bpermute_b32 v38, v28, v37
	v_and_b32_e32 v33, 0xffff0000, v5
	v_lshlrev_b32_e32 v34, 16, v6
	s_waitcnt lgkmcnt(0)
	v_add_f32_e32 v37, v37, v38
	v_fmamk_f32 v37, v37, 0x3a800000, v29
	v_rsq_f32_e32 v38, v37
	v_and_b32_e32 v37, 0xffff0000, v7
	v_pk_mul_f32 v[30:31], v[38:39], v[30:31] op_sel_hi:[0,1]
	v_pk_mul_f32 v[32:33], v[38:39], v[32:33] op_sel_hi:[0,1]
	v_pk_mul_f32 v[34:35], v[38:39], v[34:35] op_sel_hi:[0,1]
	v_pk_mul_f32 v[36:37], v[38:39], v[36:37] op_sel_hi:[0,1]
	v_pk_mul_f32 v[10:11], v[50:51], v[32:33]
	v_pk_mul_f32 v[8:9], v[48:49], v[30:31]
	v_pk_mul_f32 v[14:15], v[54:55], v[36:37]
	v_pk_mul_f32 v[12:13], v[52:53], v[34:35]
	global_store_dwordx4 v[40:41], v[8:11], off nt
	global_store_dwordx4 v[40:41], v[12:15], off offset:16 nt
	v_lshlrev_b32_e32 v30, 16, v0
	v_and_b32_e32 v31, 0xffff0000, v0
	v_lshlrev_b32_e32 v32, 16, v1
	v_and_b32_e32 v33, 0xffff0000, v1
	v_lshlrev_b32_e32 v34, 16, v2
	v_and_b32_e32 v35, 0xffff0000, v2
	v_lshlrev_b32_e32 v36, 16, v3
	v_and_b32_e32 v37, 0xffff0000, v3
	v_pk_mul_f32 v[32:33], v[38:39], v[32:33] op_sel_hi:[0,1]
	v_pk_mul_f32 v[30:31], v[38:39], v[30:31] op_sel_hi:[0,1]
	v_pk_mul_f32 v[36:37], v[38:39], v[36:37] op_sel_hi:[0,1]
	v_pk_mul_f32 v[34:35], v[38:39], v[34:35] op_sel_hi:[0,1]
	v_pk_mul_f32 v[8:9], v[56:57], v[30:31]
	v_pk_mul_f32 v[10:11], v[58:59], v[32:33]
	v_pk_mul_f32 v[12:13], v[60:61], v[34:35]
	v_pk_mul_f32 v[14:15], v[62:63], v[36:37]
	global_store_dwordx4 v[40:41], v[8:11], off offset:2048 nt
	global_store_dwordx4 v[40:41], v[12:15], off offset:2064 nt

; __device__ __forceinline__ void final_phase(CArgs* a, int gw, int NGW, int lane) {
;     ...
;         for (int rr = 0; rr < 2; ++rr) { const int m = mb + rr * NGW; if (m < M) { float s = sp[rr];
;             s += __shfl_xor(s, 1); s += __shfl_xor(s, 2); s += __shfl_xor(s, 4); s += __shfl_xor(s, 8);
;             const float r = __builtin_amdgcn_rsqf(s * (1.f / 1024.f) + EPS);
; #pragma unroll
;             for (int j = 0; j < 2; ++j) { const v4u w = raw[rr][j]; const int col = 8 * (lane + 64 * j);
;                 const f32x4 g0 = *(const f32x4*)(g + col), g1 = *(const f32x4*)(g + col + 4);
;                 const f32x4 v0 = (f32x4){__builtin_bit_cast(float, w.x << 16), __builtin_bit_cast(float, w.x & 0xffff0000u), __builtin_bit_cast(float, w.y << 16), __builtin_bit_cast(float, w.y & 0xffff0000u)};
;                 const f32x4 v1 = (f32x4){__builtin_bit_cast(float, w.z << 16), __builtin_bit_cast(float, w.z & 0xffff0000u), __builtin_bit_cast(float, w.w << 16), __builtin_bit_cast(float, w.w & 0xffff0000u)};
;                 __builtin_nontemporal_store(v0 * r * g0, (f32x4*)(X + (size_t)m * D + col)); __builtin_nontemporal_store(v1 * r * g1, (f32x4*)(X + (size_t)m * D + col + 4)); } } } }
.LBB0_1141:
	s_waitcnt vmcnt(0)
	ds_bpermute_b32 v31, v18, v30
	s_lshl_b64 s[4:5], s[8:9], 12
	v_lshl_add_u64 v[44:45], v[24:25], 0, s[4:5]
	s_andn2_b64 vcc, exec, s[2:3]
	s_waitcnt lgkmcnt(0)
	v_add_f32_e32 v30, v30, v31
	ds_bpermute_b32 v31, v26, v30
	s_waitcnt lgkmcnt(0)
	v_add_f32_e32 v40, v30, v31
	ds_bpermute_b32 v41, v27, v40
	v_lshlrev_b32_e32 v30, 16, v12
	v_and_b32_e32 v31, 0xffff0000, v12
	v_lshlrev_b32_e32 v12, 16, v13
	v_and_b32_e32 v13, 0xffff0000, v13
	s_waitcnt lgkmcnt(0)
	v_add_f32_e32 v42, v40, v41
	ds_bpermute_b32 v43, v28, v42
	v_lshlrev_b32_e32 v40, 16, v14
	v_and_b32_e32 v41, 0xffff0000, v14
	s_waitcnt lgkmcnt(0)
	v_add_f32_e32 v14, v42, v43
	v_fmamk_f32 v14, v14, 0x3a800000, v29
	v_rsq_f32_e32 v42, v14
	v_lshlrev_b32_e32 v14, 16, v15
	v_and_b32_e32 v15, 0xffff0000, v15
	v_pk_mul_f32 v[30:31], v[42:43], v[30:31] op_sel_hi:[0,1]
	v_pk_mul_f32 v[12:13], v[42:43], v[12:13] op_sel_hi:[0,1]
	v_pk_mul_f32 v[40:41], v[42:43], v[40:41] op_sel_hi:[0,1]
	v_pk_mul_f32 v[46:47], v[42:43], v[14:15] op_sel_hi:[0,1]
	v_pk_mul_f32 v[14:15], v[50:51], v[12:13]
	v_pk_mul_f32 v[12:13], v[48:49], v[30:31]
	v_pk_mul_f32 v[32:33], v[54:55], v[46:47]
	v_pk_mul_f32 v[30:31], v[52:53], v[40:41]
	global_store_dwordx4 v[44:45], v[12:15], off nt
	global_store_dwordx4 v[44:45], v[30:33], off offset:16 nt
	v_lshlrev_b32_e32 v34, 16, v8
	v_and_b32_e32 v35, 0xffff0000, v8
	v_lshlrev_b32_e32 v8, 16, v9
	v_and_b32_e32 v9, 0xffff0000, v9
	v_lshlrev_b32_e32 v36, 16, v10
	v_and_b32_e32 v37, 0xffff0000, v10
	v_lshlrev_b32_e32 v10, 16, v11
	v_and_b32_e32 v11, 0xffff0000, v11
	v_pk_mul_f32 v[38:39], v[42:43], v[8:9] op_sel_hi:[0,1]
	v_pk_mul_f32 v[8:9], v[42:43], v[34:35] op_sel_hi:[0,1]
	v_pk_mul_f32 v[34:35], v[42:43], v[10:11] op_sel_hi:[0,1]
	v_pk_mul_f32 v[36:37], v[42:43], v[36:37] op_sel_hi:[0,1]
	v_pk_mul_f32 v[8:9], v[56:57], v[8:9]
	v_pk_mul_f32 v[10:11], v[58:59], v[38:39]
	v_pk_mul_f32 v[12:13], v[60:61], v[36:37]
	v_pk_mul_f32 v[14:15], v[62:63], v[34:35]
	global_store_dwordx4 v[44:45], v[8:11], off offset:2048 nt
	global_store_dwordx4 v[44:45], v[12:15], off offset:2064 nt
	s_cbranch_vccnz .LBB0_1143
	s_cbranch_execnz .LBB0_1138
	s_branch .LBB0_1137
